# P8 epilogue: per-row scale table kept in LDS across consecutive tiles that share the row panel; loads, wait and recompute skipped when pm is unchanged
# baseline (speedup 1.0000x reference)
.LBB0_731:
	s_add_u32 s4, s76, 0x3ca00000
	s_addc_u32 s5, s77, 0
	s_cmp_lt_i32 s78, 13
	s_cselect_b64 s[2:3], -1, 0
	s_cmp_gt_i32 s79, 12
	s_cselect_b64 s[6:7], -1, 0
	s_and_b64 s[2:3], s[2:3], s[6:7]
	s_andn2_b64 vcc, exec, s[2:3]
	s_cbranch_vccnz .LBB0_855
	s_mov_b32 s98, -1
	v_mov_b32_e32 v0, v214
	s_mov_b32 s18, s73
	s_mov_b32 s19, s69
	s_waitcnt vmcnt(0)
	v_mov_b32_e32 v14, v214
	s_cmpk_lt_i32 s19, 0x1600
	s_cselect_b64 s[2:3], -1, 0
	s_cmpk_gt_i32 s19, 0x15ff
	v_readfirstlane_b32 s14, v14
	s_cbranch_scc1 .LBB0_735
	s_ashr_i32 s6, s19, 31
	s_lshr_b32 s6, s6, 29
	s_add_i32 s6, s19, s6
	s_ashr_i32 s7, s6, 3
	s_and_b32 s6, s6, -8
	s_sub_i32 s6, s19, s6
	s_cmp_lt_i32 s6, 0
	s_movk_i32 s8, 0x2c1
	s_cselect_b32 s8, s8, 0x2c0
	s_mul_i32 s6, s6, s8
	s_add_i32 s6, s6, s7
	s_mul_hi_i32 s7, s6, 0x2e8ba2e9
	s_lshr_b32 s8, s7, 31
	s_ashr_i32 s7, s7, 5
	s_add_i32 s7, s7, s8
	s_lshl_b32 s8, s7, 3
	s_mulk_i32 s7, 0xb0
	s_sub_i32 s6, s6, s7
	s_bfe_u32 s7, s6, 0x3001c
	s_add_i32 s7, s6, s7
	s_sext_i32_i16 s9, s7
	s_and_b32 s7, s7, 0xfff8
	s_sub_i32 s6, s6, s7
	s_sext_i32_i16 s6, s6
	s_add_i32 s10, s8, s6
	s_ashr_i32 s12, s9, 3
	s_andn2_b64 vcc, exec, s[2:3]
	s_cbranch_vccz .LBB0_736

.LBB0_744:
	ds_read_b128 v[80:83], v226
	ds_read_b128 v[84:87], v226 offset:1024
	ds_read_b128 v[88:91], v226 offset:2048
	ds_read_b128 v[92:95], v226 offset:3072
	ds_read_b128 v[128:131], v227
	ds_read_b128 v[132:135], v227 offset:1024
	ds_read_b128 v[152:155], v227 offset:2048
	ds_read_b128 v[156:159], v227 offset:3072
	s_add_u32 s26, s46, 0xfffc0080
	s_addc_u32 s27, s47, -1
	s_cmp_eq_u32 s25, 12
	s_cselect_b32 s89, s11, s27
	s_cselect_b32 s88, s14, s26
	s_cselect_b32 s49, s15, s24
	s_cselect_b32 s48, s16, s17
	s_add_i32 m0, s13, 0xc000
	ds_read_b128 v[160:163], v228
	ds_read_b128 v[164:167], v228 offset:1024
	ds_read_b128 v[168:171], v228 offset:2048
	ds_read_b128 v[172:175], v228 offset:3072
	ds_read_b128 v[192:195], v228 offset:4096
	ds_read_b128 v[196:199], v228 offset:5120
	ds_read_b128 v[200:203], v228 offset:6144
	ds_read_b128 v[204:207], v228 offset:7168
	global_load_lds_dwordx4 v184, s[46:47]
	s_add_i32 m0, s13, 0xe000
	s_nop 0
	global_load_lds_dwordx4 v186, s[46:47]
	s_waitcnt vmcnt(8)
	s_waitcnt lgkmcnt(0)
	s_barrier
	s_setprio 1
	s_waitcnt lgkmcnt(0)
	v_mfma_f32_16x16x32_bf16 v[76:79], v[80:83], v[160:163], v[76:79]
	v_mfma_f32_16x16x32_bf16 v[64:67], v[88:91], v[160:163], v[64:67]
	v_mfma_f32_16x16x32_bf16 v[148:151], v[80:83], v[168:171], v[148:151]
	v_mfma_f32_16x16x32_bf16 v[140:143], v[88:91], v[168:171], v[140:143]
	v_mfma_f32_16x16x32_bf16 v[124:127], v[80:83], v[192:195], v[124:127]
	v_mfma_f32_16x16x32_bf16 v[120:123], v[88:91], v[192:195], v[120:123]
	v_mfma_f32_16x16x32_bf16 v[72:75], v[80:83], v[200:203], v[72:75]
	v_mfma_f32_16x16x32_bf16 v[60:63], v[88:91], v[200:203], v[60:63]
	v_mfma_f32_16x16x32_bf16 v[76:79], v[84:87], v[164:167], v[76:79]
	v_mfma_f32_16x16x32_bf16 v[64:67], v[92:95], v[164:167], v[64:67]
	v_mfma_f32_16x16x32_bf16 v[148:151], v[84:87], v[172:175], v[148:151]
	v_mfma_f32_16x16x32_bf16 v[140:143], v[92:95], v[172:175], v[140:143]
	v_mfma_f32_16x16x32_bf16 v[124:127], v[84:87], v[196:199], v[124:127]
	v_mfma_f32_16x16x32_bf16 v[120:123], v[92:95], v[196:199], v[120:123]
	v_mfma_f32_16x16x32_bf16 v[72:75], v[84:87], v[204:207], v[72:75]
	v_mfma_f32_16x16x32_bf16 v[60:63], v[92:95], v[204:207], v[60:63]
	s_setprio 0
	s_setprio 1
	v_mfma_f32_16x16x32_bf16 v[144:147], v[128:131], v[160:163], v[144:147]
	v_mfma_f32_16x16x32_bf16 v[136:139], v[152:155], v[160:163], v[136:139]
	v_mfma_f32_16x16x32_bf16 v[116:119], v[128:131], v[168:171], v[116:119]
	v_mfma_f32_16x16x32_bf16 v[112:115], v[152:155], v[168:171], v[112:115]
	v_mfma_f32_16x16x32_bf16 v[108:111], v[128:131], v[192:195], v[108:111]
	v_mfma_f32_16x16x32_bf16 v[104:107], v[152:155], v[192:195], v[104:107]
	v_mfma_f32_16x16x32_bf16 v[100:103], v[128:131], v[200:203], v[100:103]
	v_mfma_f32_16x16x32_bf16 v[96:99], v[152:155], v[200:203], v[96:99]
	v_mfma_f32_16x16x32_bf16 v[144:147], v[132:135], v[164:167], v[144:147]
	v_mfma_f32_16x16x32_bf16 v[136:139], v[156:159], v[164:167], v[136:139]
	v_mfma_f32_16x16x32_bf16 v[116:119], v[132:135], v[172:175], v[116:119]
	v_mfma_f32_16x16x32_bf16 v[112:115], v[156:159], v[172:175], v[112:115]
	v_mfma_f32_16x16x32_bf16 v[108:111], v[132:135], v[196:199], v[108:111]
	v_mfma_f32_16x16x32_bf16 v[104:107], v[156:159], v[196:199], v[104:107]
	v_mfma_f32_16x16x32_bf16 v[100:103], v[132:135], v[204:207], v[100:103]
	v_mfma_f32_16x16x32_bf16 v[96:99], v[156:159], v[204:207], v[96:99]
	s_setprio 0
	s_barrier
	s_add_i32 s26, s3, s20
	s_mov_b32 m0, s26
	ds_read_b128 v[160:163], v228 offset:16384
	ds_read_b128 v[164:167], v228 offset:17408
	ds_read_b128 v[168:171], v228 offset:18432
	ds_read_b128 v[172:175], v228 offset:19456
	ds_read_b128 v[192:195], v228 offset:20480
	ds_read_b128 v[196:199], v228 offset:21504
	ds_read_b128 v[200:203], v228 offset:22528
	ds_read_b128 v[204:207], v228 offset:23552
	global_load_lds_dwordx4 v178, s[48:49]
	s_add_i32 m0, s26, 0x2000
	s_add_u32 s26, s48, 0x40000
	s_addc_u32 s27, s49, 0
	s_add_i32 s28, s93, s20
	global_load_lds_dwordx4 v182, s[48:49]
	s_mov_b32 m0, s28
	s_nop 0
	global_load_lds_dwordx4 v178, s[26:27]
	s_add_i32 m0, s28, 0x2000
	s_nop 0
	global_load_lds_dwordx4 v182, s[26:27]
	s_mov_b32 m0, s13
	s_nop 0
	global_load_lds_dwordx4 v176, s[88:89]
	s_mov_b32 m0, s21
	s_nop 0
	global_load_lds_dwordx4 v180, s[88:89]
	s_waitcnt vmcnt(8)
	s_waitcnt lgkmcnt(0)
	s_barrier
	s_setprio 1
	s_waitcnt lgkmcnt(0)
	v_mfma_f32_16x16x32_bf16 v[68:71], v[80:83], v[160:163], v[68:71]
	v_mfma_f32_16x16x32_bf16 v[36:39], v[88:91], v[160:163], v[36:39]
	v_mfma_f32_16x16x32_bf16 v[52:55], v[80:83], v[168:171], v[52:55]
	v_mfma_f32_16x16x32_bf16 v[44:47], v[88:91], v[168:171], v[44:47]
	v_mfma_f32_16x16x32_bf16 v[28:31], v[80:83], v[192:195], v[28:31]
	v_mfma_f32_16x16x32_bf16 v[24:27], v[88:91], v[192:195], v[24:27]
	v_mfma_f32_16x16x32_bf16 v[56:59], v[80:83], v[200:203], v[56:59]
	v_mfma_f32_16x16x32_bf16 v[32:35], v[88:91], v[200:203], v[32:35]
	v_mfma_f32_16x16x32_bf16 v[68:71], v[84:87], v[164:167], v[68:71]
	v_mfma_f32_16x16x32_bf16 v[36:39], v[92:95], v[164:167], v[36:39]
	v_mfma_f32_16x16x32_bf16 v[52:55], v[84:87], v[172:175], v[52:55]
	v_mfma_f32_16x16x32_bf16 v[44:47], v[92:95], v[172:175], v[44:47]
	v_mfma_f32_16x16x32_bf16 v[28:31], v[84:87], v[196:199], v[28:31]
	v_mfma_f32_16x16x32_bf16 v[24:27], v[92:95], v[196:199], v[24:27]
	v_mfma_f32_16x16x32_bf16 v[56:59], v[84:87], v[204:207], v[56:59]
	v_mfma_f32_16x16x32_bf16 v[32:35], v[92:95], v[204:207], v[32:35]
	s_setprio 0
	s_setprio 1
	v_mfma_f32_16x16x32_bf16 v[48:51], v[128:131], v[160:163], v[48:51]
	v_mfma_f32_16x16x32_bf16 v[40:43], v[152:155], v[160:163], v[40:43]
	v_mfma_f32_16x16x32_bf16 v[20:23], v[128:131], v[168:171], v[20:23]
	v_mfma_f32_16x16x32_bf16 v[16:19], v[152:155], v[168:171], v[16:19]
	v_mfma_f32_16x16x32_bf16 v[12:15], v[128:131], v[192:195], v[12:15]
	v_mfma_f32_16x16x32_bf16 v[8:11], v[152:155], v[192:195], v[8:11]
	v_mfma_f32_16x16x32_bf16 v[4:7], v[128:131], v[200:203], v[4:7]
	v_mfma_f32_16x16x32_bf16 v[0:3], v[152:155], v[200:203], v[0:3]
	v_mfma_f32_16x16x32_bf16 v[48:51], v[132:135], v[164:167], v[48:51]
	v_mfma_f32_16x16x32_bf16 v[40:43], v[156:159], v[164:167], v[40:43]
	v_mfma_f32_16x16x32_bf16 v[20:23], v[132:135], v[172:175], v[20:23]
	v_mfma_f32_16x16x32_bf16 v[16:19], v[156:159], v[172:175], v[16:19]
	v_mfma_f32_16x16x32_bf16 v[12:15], v[132:135], v[196:199], v[12:15]
	v_mfma_f32_16x16x32_bf16 v[8:11], v[156:159], v[196:199], v[8:11]
	v_mfma_f32_16x16x32_bf16 v[4:7], v[132:135], v[204:207], v[4:7]
	v_mfma_f32_16x16x32_bf16 v[0:3], v[156:159], v[204:207], v[0:3]
	s_setprio 0
	s_barrier
	s_add_i32 s28, 0, 0x18000
	s_add_i32 s29, 0, 0x1c000
	v_add_u32_e32 v92, s28, v218
	v_add_u32_e32 v156, s29, v218
	ds_read_b128 v[80:83], v92
	ds_read_b128 v[84:87], v92 offset:1024
	ds_read_b128 v[88:91], v92 offset:2048
	ds_read_b128 v[92:95], v92 offset:3072
	ds_read_b128 v[128:131], v156
	ds_read_b128 v[132:135], v156 offset:1024
	ds_read_b128 v[152:155], v156 offset:2048
	ds_read_b128 v[156:159], v156 offset:3072
	s_add_u32 s26, s88, 0x40000
	s_addc_u32 s27, s89, 0
	s_mov_b32 m0, s22
	ds_read_b128 v[160:163], v228 offset:32768
	ds_read_b128 v[164:167], v228 offset:33792
	ds_read_b128 v[168:171], v228 offset:34816
	ds_read_b128 v[172:175], v228 offset:35840
	ds_read_b128 v[192:195], v228 offset:36864
	ds_read_b128 v[196:199], v228 offset:37888
	ds_read_b128 v[200:203], v228 offset:38912
	ds_read_b128 v[204:207], v228 offset:39936
	global_load_lds_dwordx4 v176, s[26:27]
	s_mov_b32 m0, s23
	s_nop 0
	global_load_lds_dwordx4 v180, s[26:27]
	s_waitcnt vmcnt(8)
	s_waitcnt lgkmcnt(0)
	s_barrier
	s_setprio 1
	s_waitcnt lgkmcnt(0)
	v_mfma_f32_16x16x32_bf16 v[76:79], v[80:83], v[160:163], v[76:79]
	v_mfma_f32_16x16x32_bf16 v[64:67], v[88:91], v[160:163], v[64:67]
	v_mfma_f32_16x16x32_bf16 v[148:151], v[80:83], v[168:171], v[148:151]
	v_mfma_f32_16x16x32_bf16 v[140:143], v[88:91], v[168:171], v[140:143]
	v_mfma_f32_16x16x32_bf16 v[124:127], v[80:83], v[192:195], v[124:127]
	v_mfma_f32_16x16x32_bf16 v[120:123], v[88:91], v[192:195], v[120:123]
	v_mfma_f32_16x16x32_bf16 v[72:75], v[80:83], v[200:203], v[72:75]
	v_mfma_f32_16x16x32_bf16 v[60:63], v[88:91], v[200:203], v[60:63]
	v_mfma_f32_16x16x32_bf16 v[76:79], v[84:87], v[164:167], v[76:79]
	v_mfma_f32_16x16x32_bf16 v[64:67], v[92:95], v[164:167], v[64:67]
	v_mfma_f32_16x16x32_bf16 v[148:151], v[84:87], v[172:175], v[148:151]
	v_mfma_f32_16x16x32_bf16 v[140:143], v[92:95], v[172:175], v[140:143]
	v_mfma_f32_16x16x32_bf16 v[124:127], v[84:87], v[196:199], v[124:127]
	v_mfma_f32_16x16x32_bf16 v[120:123], v[92:95], v[196:199], v[120:123]
	v_mfma_f32_16x16x32_bf16 v[72:75], v[84:87], v[204:207], v[72:75]
	v_mfma_f32_16x16x32_bf16 v[60:63], v[92:95], v[204:207], v[60:63]
	s_setprio 0
	s_setprio 1
	v_mfma_f32_16x16x32_bf16 v[144:147], v[128:131], v[160:163], v[144:147]
	v_mfma_f32_16x16x32_bf16 v[136:139], v[152:155], v[160:163], v[136:139]
	v_mfma_f32_16x16x32_bf16 v[116:119], v[128:131], v[168:171], v[116:119]
	v_mfma_f32_16x16x32_bf16 v[112:115], v[152:155], v[168:171], v[112:115]
	v_mfma_f32_16x16x32_bf16 v[108:111], v[128:131], v[192:195], v[108:111]
	v_mfma_f32_16x16x32_bf16 v[104:107], v[152:155], v[192:195], v[104:107]
	v_mfma_f32_16x16x32_bf16 v[100:103], v[128:131], v[200:203], v[100:103]
	v_mfma_f32_16x16x32_bf16 v[96:99], v[152:155], v[200:203], v[96:99]
	v_mfma_f32_16x16x32_bf16 v[144:147], v[132:135], v[164:167], v[144:147]
	v_mfma_f32_16x16x32_bf16 v[136:139], v[156:159], v[164:167], v[136:139]
	v_mfma_f32_16x16x32_bf16 v[116:119], v[132:135], v[172:175], v[116:119]
	v_mfma_f32_16x16x32_bf16 v[112:115], v[156:159], v[172:175], v[112:115]
	v_mfma_f32_16x16x32_bf16 v[108:111], v[132:135], v[196:199], v[108:111]
	v_mfma_f32_16x16x32_bf16 v[104:107], v[156:159], v[196:199], v[104:107]
	v_mfma_f32_16x16x32_bf16 v[100:103], v[132:135], v[204:207], v[100:103]
	v_mfma_f32_16x16x32_bf16 v[96:99], v[156:159], v[204:207], v[96:99]
	s_setprio 0
	s_barrier
	s_add_i32 m0, s28, s20
	s_add_u32 s26, s48, 0x80
	s_addc_u32 s27, s49, 0
	ds_read_b128 v[160:163], v228 offset:49152
	ds_read_b128 v[164:167], v228 offset:50176
	ds_read_b128 v[168:171], v228 offset:51200
	ds_read_b128 v[172:175], v228 offset:52224
	ds_read_b128 v[192:195], v228 offset:53248
	ds_read_b128 v[196:199], v228 offset:54272
	ds_read_b128 v[200:203], v228 offset:55296
	ds_read_b128 v[204:207], v228 offset:56320
	global_load_lds_dwordx4 v178, s[26:27]
	s_add_i32 m0, m0, 0x2000
	s_add_i32 s28, s29, s20
	global_load_lds_dwordx4 v182, s[26:27]
	s_add_u32 s26, s26, 0x40000
	s_addc_u32 s27, s27, 0
	s_mov_b32 m0, s28
	s_nop 0
	global_load_lds_dwordx4 v178, s[26:27]
	s_add_i32 m0, s28, 0x2000
	s_nop 0
	global_load_lds_dwordx4 v182, s[26:27]
	s_add_u32 s26, s88, 0x80
	s_addc_u32 s27, s89, 0
	s_mov_b32 m0, s71
	s_nop 0
	global_load_lds_dwordx4 v176, s[26:27]
	s_mov_b32 m0, s73
	s_nop 0
	global_load_lds_dwordx4 v180, s[26:27]
	s_add_u32 s26, s48, 0x40080
	s_addc_u32 s27, s49, 0
	s_waitcnt vmcnt(8)
	s_waitcnt lgkmcnt(0)
	s_barrier
	s_setprio 1
	s_waitcnt lgkmcnt(0)
	v_mfma_f32_16x16x32_bf16 v[68:71], v[80:83], v[160:163], v[68:71]
	v_mfma_f32_16x16x32_bf16 v[36:39], v[88:91], v[160:163], v[36:39]
	v_mfma_f32_16x16x32_bf16 v[52:55], v[80:83], v[168:171], v[52:55]
	v_mfma_f32_16x16x32_bf16 v[44:47], v[88:91], v[168:171], v[44:47]
	v_mfma_f32_16x16x32_bf16 v[28:31], v[80:83], v[192:195], v[28:31]
	v_mfma_f32_16x16x32_bf16 v[24:27], v[88:91], v[192:195], v[24:27]
	v_mfma_f32_16x16x32_bf16 v[56:59], v[80:83], v[200:203], v[56:59]
	v_mfma_f32_16x16x32_bf16 v[32:35], v[88:91], v[200:203], v[32:35]
	v_mfma_f32_16x16x32_bf16 v[68:71], v[84:87], v[164:167], v[68:71]
	v_mfma_f32_16x16x32_bf16 v[36:39], v[92:95], v[164:167], v[36:39]
	v_mfma_f32_16x16x32_bf16 v[52:55], v[84:87], v[172:175], v[52:55]
	v_mfma_f32_16x16x32_bf16 v[44:47], v[92:95], v[172:175], v[44:47]
	v_mfma_f32_16x16x32_bf16 v[28:31], v[84:87], v[196:199], v[28:31]
	v_mfma_f32_16x16x32_bf16 v[24:27], v[92:95], v[196:199], v[24:27]
	v_mfma_f32_16x16x32_bf16 v[56:59], v[84:87], v[204:207], v[56:59]
	v_mfma_f32_16x16x32_bf16 v[32:35], v[92:95], v[204:207], v[32:35]
	s_setprio 0
	s_setprio 1
	v_mfma_f32_16x16x32_bf16 v[48:51], v[128:131], v[160:163], v[48:51]
	v_mfma_f32_16x16x32_bf16 v[40:43], v[152:155], v[160:163], v[40:43]
	v_mfma_f32_16x16x32_bf16 v[20:23], v[128:131], v[168:171], v[20:23]
	v_mfma_f32_16x16x32_bf16 v[16:19], v[152:155], v[168:171], v[16:19]
	v_mfma_f32_16x16x32_bf16 v[12:15], v[128:131], v[192:195], v[12:15]
	v_mfma_f32_16x16x32_bf16 v[8:11], v[152:155], v[192:195], v[8:11]
	v_mfma_f32_16x16x32_bf16 v[4:7], v[128:131], v[200:203], v[4:7]
	v_mfma_f32_16x16x32_bf16 v[0:3], v[152:155], v[200:203], v[0:3]
	v_mfma_f32_16x16x32_bf16 v[48:51], v[132:135], v[164:167], v[48:51]
	v_mfma_f32_16x16x32_bf16 v[40:43], v[156:159], v[164:167], v[40:43]
	v_mfma_f32_16x16x32_bf16 v[20:23], v[132:135], v[172:175], v[20:23]
	v_mfma_f32_16x16x32_bf16 v[16:19], v[156:159], v[172:175], v[16:19]
	v_mfma_f32_16x16x32_bf16 v[12:15], v[132:135], v[196:199], v[12:15]
	v_mfma_f32_16x16x32_bf16 v[8:11], v[156:159], v[196:199], v[8:11]
	v_mfma_f32_16x16x32_bf16 v[4:7], v[132:135], v[204:207], v[4:7]
	v_mfma_f32_16x16x32_bf16 v[0:3], v[156:159], v[204:207], v[0:3]
	s_setprio 0
	s_barrier
	s_add_i32 s25, s25, 2
	s_add_u32 s46, s46, 0x100
	s_addc_u32 s47, s47, 0
	s_add_u32 s17, s17, 0x100
	s_addc_u32 s24, s24, 0
	s_cmp_gt_u32 s25, 13
	s_cbranch_scc0 .LBB0_744
	v_mov_b32_e32 v80, v214
	s_movk_i32 s14, 0x100
	s_lshl_b32 s11, s10, 8
	s_nop 0
	s_cmp_eq_u32 s10, s98
	s_cbranch_scc1 .Lp8_rsl_keep1
	v_cmp_gt_i32_e32 vcc, s14, v80
	s_and_saveexec_b64 s[46:47], vcc
	s_cbranch_execz .Lp8_noss
	v_add_u32_e32 v82, s11, v80
	v_ashrrev_i32_e32 v83, 31, v82
	v_lshlrev_b64 v[82:83], 6, v[82:83]
	v_lshl_add_u64 v[94:95], s[0:1], 0, v[82:83]
	global_load_dwordx4 v[82:85], v[94:95], off
	global_load_dwordx4 v[86:89], v[94:95], off offset:16
	global_load_dwordx4 v[90:93], v[94:95], off offset:32
	global_load_dwordx4 v[128:131], v[94:95], off offset:48
.Lp8_noss:
	s_or_b64 exec, exec, s[46:47]
.Lp8_rsl_keep1:
	s_and_b64 vcc, exec, s[8:9]
	s_cbranch_vccz .LBB0_747
	s_barrier
.LBB0_747:
	s_cmp_eq_u32 s10, s98
	s_mov_b32 s98, s10
	s_cbranch_scc1 .Lp8_rsl_keep2
	v_cmp_gt_i32_e32 vcc, s14, v80
	s_and_saveexec_b64 s[46:47], vcc
	s_cbranch_execz .LBB0_749
	s_mov_b32 s14, 0x800000
	v_lshl_add_u32 v80, v80, 2, 0
	v_add_u32_e32 v80, 0x21000, v80
	s_waitcnt vmcnt(0)
	v_pk_add_f32 v[84:85], v[84:85], v[88:89]
	v_pk_add_f32 v[82:83], v[82:83], v[86:87]
	v_pk_add_f32 v[86:87], v[92:93], v[130:131]
	v_pk_add_f32 v[88:89], v[90:91], v[128:129]
	v_pk_add_f32 v[84:85], v[84:85], v[86:87]
	v_pk_add_f32 v[82:83], v[82:83], v[88:89]
	s_nop 0
	v_pk_mov_b32 v[86:87], v[82:83], v[84:85] op_sel:[1,0]
	v_mov_b32_e32 v83, v85
	v_pk_add_f32 v[82:83], v[86:87], v[82:83]
	s_nop 0
	v_add_f32_e32 v81, v82, v83
	v_fmamk_f32 v81, v81, 0x3a800000, v229
	v_mul_f32_e32 v82, 0x4b800000, v81
	v_cmp_gt_f32_e32 vcc, s14, v81
	s_nop 1
	v_cndmask_b32_e32 v81, v81, v82, vcc
	v_rsq_f32_e32 v81, v81
	s_nop 0
	v_mul_f32_e32 v82, 0x45800000, v81
	v_cndmask_b32_e32 v81, v81, v82, vcc
	ds_write_b32 v80, v81

.Lp8_rsl_keep2:
	s_waitcnt lgkmcnt(0)
	s_barrier
	ds_read2_b32 v[212:213], v221 offset1:16
	ds_read2_b32 v[202:203], v221 offset0:32 offset1:48
	ds_read2_b32 v[200:201], v221 offset0:128 offset1:144
	ds_read2_b32 v[196:197], v221 offset0:160 offset1:176
	v_cmp_lt_i32_e32 vcc, 14, v216
	s_waitcnt lgkmcnt(0)
	v_mov_b32_e32 v208, v213
	v_mov_b32_e32 v204, v203
	v_mov_b32_e32 v198, v201
	v_mov_b32_e32 v194, v197
	s_mov_b64 s[46:47], 0
	s_and_saveexec_b64 s[14:15], vcc
	s_xor_b64 s[14:15], exec, s[14:15]
	s_mov_b64 s[46:47], exec
	s_or_saveexec_b64 s[48:49], s[14:15]
	v_pk_mul_f32 v[132:133], v[72:73], v[204:205] op_sel_hi:[1,0]
	v_pk_mul_f32 v[128:129], v[60:61], v[204:205] op_sel_hi:[1,0]
	v_pk_mul_f32 v[162:163], v[66:67], v[212:213] op_sel_hi:[1,0]
	v_pk_mul_f32 v[160:161], v[64:65], v[212:213] op_sel_hi:[1,0]
	v_pk_mul_f32 v[134:135], v[74:75], v[204:205] op_sel_hi:[1,0]
	v_pk_mul_f32 v[130:131], v[62:63], v[204:205] op_sel_hi:[1,0]
	v_mov_b64_e32 v[64:65], v[132:133]
	v_mov_b64_e32 v[60:61], v[128:129]
	v_pk_mul_f32 v[166:167], v[78:79], v[212:213] op_sel_hi:[1,0]
	v_pk_mul_f32 v[164:165], v[76:77], v[212:213] op_sel_hi:[1,0]
	v_mov_b32_e32 v72, s91
	v_mov_b64_e32 v[62:63], v[130:131]
	v_mov_b64_e32 v[66:67], v[134:135]
	s_xor_b64 exec, exec, s[48:49]
	v_cmp_eq_u32_e32 vcc, 0, v216
	s_andn2_b64 s[14:15], s[46:47], exec
	s_and_b64 s[16:17], vcc, exec
	v_mov_b64_e32 v[60:61], v[160:161]
	v_mov_b64_e32 v[64:65], v[164:165]
	v_mov_b32_e32 v72, s34
	s_or_b64 s[46:47], s[14:15], s[16:17]
	v_mov_b64_e32 v[62:63], v[162:163]
	v_mov_b64_e32 v[66:67], v[166:167]
	s_or_b64 exec, exec, s[48:49]
	v_pk_mul_f32 v[94:95], v[70:71], v[200:201] op_sel_hi:[1,0]
	v_pk_mul_f32 v[92:93], v[68:69], v[200:201] op_sel_hi:[1,0]
	v_pk_mul_f32 v[90:91], v[38:39], v[200:201] op_sel_hi:[1,0]
	v_pk_mul_f32 v[88:89], v[36:37], v[200:201] op_sel_hi:[1,0]
	v_pk_mul_f32 v[38:39], v[58:59], v[194:195] op_sel_hi:[1,0]
	v_pk_mul_f32 v[36:37], v[56:57], v[194:195] op_sel_hi:[1,0]
	v_pk_mul_f32 v[34:35], v[34:35], v[194:195] op_sel_hi:[1,0]
	v_pk_mul_f32 v[32:33], v[32:33], v[194:195] op_sel_hi:[1,0]
	s_and_saveexec_b64 s[48:49], s[46:47]
	s_cbranch_execz .LBB0_760
	v_lshl_add_u32 v56, v72, 2, v220
	ds_write_b128 v56, v[64:67]
	ds_write_b128 v56, v[60:63] offset:16
	v_readlane_b32 s14, v255, 25
	v_mov_b64_e32 v[58:59], v[34:35]
	v_mov_b64_e32 v[62:63], v[38:39]
	v_cmp_gt_i32_e32 vcc, 15, v216
	s_mov_b64 s[88:89], -1
	v_mov_b32_e32 v64, s14
	v_mov_b64_e32 v[56:57], v[32:33]
	v_mov_b64_e32 v[60:61], v[36:37]
	s_and_saveexec_b64 s[46:47], vcc
	s_cbranch_execz .LBB0_758
	v_cmp_eq_u32_e32 vcc, 0, v216
	s_mov_b64 s[14:15], 0
	s_and_saveexec_b64 s[16:17], vcc
	s_mov_b64 s[14:15], exec
	s_or_b64 exec, exec, s[16:17]
	v_mov_b64_e32 v[56:57], v[88:89]
	v_mov_b64_e32 v[60:61], v[92:93]
	v_mov_b32_e32 v64, s35
	s_orn2_b64 s[88:89], s[14:15], exec
	v_mov_b64_e32 v[58:59], v[90:91]
	v_mov_b64_e32 v[62:63], v[94:95]
